# sample-row LayerNorm (P2, P9, P14): wait counts let the next row's prefetch stay in flight while a row is normalised
# baseline (speedup 1.0000x reference)
; __device__ __forceinline__ f32x4 unpack4(u32x2 u) { return (f32x4){__uint_as_float(u.x << 16), __uint_as_float(u.x & 0xffff0000u), __uint_as_float(u.y << 16), __uint_as_float(u.y & 0xffff0000u)}; }
; __device__ __forceinline__ u32x2 pack4(f32x4 v) { u32x2 r; r.x = cvt_pk_bf16(v.x, v.y); r.y = cvt_pk_bf16(v.z, v.w); return r; }
; __device__ __forceinline__ void ln_pass(const bf16_t* PRE, const float* g, const float* b, float* Hf, bf16_t* HB, int gw, int ngw, int lane, int row_end = MT) {
;     ...
;     while (row < row_end) {
;         const int nrow = row + ngw;
;         if (nrow < row_end) {
; #pragma unroll
;             for (int j = 0; j < 4; ++j) qn[j] = *(const u32x2*)(PRE + (size_t)nrow * D + 4 * lane + 256 * j);
;         }
;         f32x4 v[4]; float s = 0.f;
; #pragma unroll
;         for (int j = 0; j < 4; ++j) { v[j] = unpack4(q[j]); s += (v[j].x + v[j].y) + (v[j].z + v[j].w); }
;         const float mean = wave_sum(s) * (1.f / D); float s2 = 0.f;
; #pragma unroll
;         for (int j = 0; j < 4; ++j) { v[j] = v[j] - mean; s2 += (v[j].x * v[j].x + v[j].y * v[j].y) + (v[j].z * v[j].z + v[j].w * v[j].w); }
;         const float rstd = 1.0f / sqrtf(wave_sum(s2) * (1.f / D) + LN_EPS);
; #pragma unroll
;         for (int j = 0; j < 4; ++j) { const f32x4 o = v[j] * rstd * gv[j] + bv[j];
;             if (Hf) *(f32x4*)(Hf + (size_t)row * D + 256 * j + 4 * lane) = o;
;             if (HB) *(u32x2*)(HB + (size_t)row * D + 256 * j + 4 * lane) = pack4(o); }
; #pragma unroll
;         for (int j = 0; j < 4; ++j) q[j] = qn[j];
;         row = nrow;
.LBB0_442:
	s_waitcnt vmcnt(7)
	v_lshlrev_b32_e32 v59, 16, v49
	v_lshlrev_b32_e32 v58, 16, v48
	v_and_b32_e32 v49, 0xffff0000, v49
	v_and_b32_e32 v48, 0xffff0000, v48
	s_waitcnt vmcnt(6)
	v_lshlrev_b32_e32 v63, 16, v47
	v_lshlrev_b32_e32 v62, 16, v46
	v_and_b32_e32 v47, 0xffff0000, v47
	v_and_b32_e32 v46, 0xffff0000, v46
	v_pk_add_f32 v[60:61], v[58:59], v[48:49]
	v_pk_add_f32 v[64:65], v[62:63], v[46:47]
	v_add_f32_e32 v60, v60, v61
	v_pk_add_f32 v[64:65], v[64:65], v[64:65] op_sel_hi:[0,1]
	s_waitcnt vmcnt(5)
	v_lshlrev_b32_e32 v66, 16, v44
	v_and_b32_e32 v67, 0xffff0000, v44
	v_lshlrev_b32_e32 v44, 16, v45
	v_and_b32_e32 v45, 0xffff0000, v45
	v_add_f32_e32 v61, 0, v60
	v_add_f32_e32 v69, v66, v67
	v_add_f32_e32 v71, v44, v45
	s_waitcnt vmcnt(4)
	v_lshlrev_b32_e32 v68, 16, v42
	v_and_b32_e32 v70, 0xffff0000, v42
	v_lshlrev_b32_e32 v64, 16, v43
	v_and_b32_e32 v60, 0xffff0000, v43
	v_pk_add_f32 v[42:43], v[68:69], v[70:71]
	v_pk_add_f32 v[72:73], v[64:65], v[60:61]
	s_nop 0
	v_pk_add_f32 v[42:43], v[42:43], v[72:73]
	s_nop 0
	v_add_f32_e32 v42, v42, v43
	s_nop 1
	v_add_f32_dpp v42, v42, v42 quad_perm:[1,0,3,2] row_mask:0xf bank_mask:0xf
	s_nop 1
	v_add_f32_dpp v42, v42, v42 quad_perm:[2,3,0,1] row_mask:0xf bank_mask:0xf
	s_nop 1
	v_add_f32_dpp v42, v42, v42 row_half_mirror row_mask:0xf bank_mask:0xf
	s_nop 1
	v_add_f32_dpp v42, v42, v42 row_mirror row_mask:0xf bank_mask:0xf
	s_nop 1
	v_add_f32_dpp v42, v42, v42 row_bcast:15 row_mask:0xa bank_mask:0xf
	s_nop 1
	v_add_f32_dpp v42, v42, v42 row_bcast:31 row_mask:0xc bank_mask:0xf
	s_nop 1
	v_readlane_b32 s100, v42, 63
	s_nop 1
	v_mov_b32_e32 v61, s100
	v_fmac_f32_e32 v48, 0xba800000, v61
	v_fmac_f32_e32 v49, 0xba800000, v61
	v_fmac_f32_e32 v59, 0xba800000, v61
	v_fmac_f32_e32 v58, 0xba800000, v61
	v_mov_b32_e32 v42, v59
	v_mov_b32_e32 v43, v49
	v_mov_b32_e32 v59, v48
	v_pk_mul_f32 v[72:73], v[42:43], v[42:43]
	v_pk_mul_f32 v[48:49], v[58:59], v[58:59]
	v_fmac_f32_e32 v46, 0xba800000, v61
	v_fmac_f32_e32 v47, 0xba800000, v61
	v_fmac_f32_e32 v63, 0xba800000, v61
	v_pk_mov_b32 v[74:75], v[48:49], v[72:73] op_sel:[1,0]
	v_mov_b32_e32 v49, v73
	v_fmac_f32_e32 v62, 0xba800000, v61
	v_mov_b32_e32 v72, v63
	v_mov_b32_e32 v73, v47
	v_mov_b32_e32 v63, v46
	v_pk_add_f32 v[48:49], v[74:75], v[48:49]
	v_pk_mul_f32 v[74:75], v[72:73], v[72:73]
	v_pk_mul_f32 v[46:47], v[62:63], v[62:63]
	v_fmac_f32_e32 v66, 0xba800000, v61
	v_pk_mov_b32 v[76:77], v[46:47], v[74:75] op_sel:[1,0]
	v_mov_b32_e32 v47, v75
	v_pk_add_f32 v[46:47], v[76:77], v[46:47]
	v_fmac_f32_e32 v67, 0xba800000, v61
	v_pk_add_f32 v[46:47], v[46:47], v[46:47] op_sel_hi:[0,1]
	v_fmac_f32_e32 v44, 0xba800000, v61
	v_mul_f32_e32 v46, v66, v66
	v_fmac_f32_e32 v45, 0xba800000, v61
	v_pk_fma_f32 v[74:75], v[66:67], v[66:67], v[46:47] op_sel_hi:[1,1,0]
	v_mul_f32_e32 v46, v44, v44
	v_pk_add_f32 v[48:49], v[48:49], v[48:49] op_sel_hi:[0,1]
	v_pk_fma_f32 v[76:77], v[44:45], v[44:45], v[46:47] op_sel_hi:[1,1,0]
	v_fmac_f32_e32 v60, 0xba800000, v61
	v_fmac_f32_e32 v64, 0xba800000, v61
	v_fmac_f32_e32 v70, 0xba800000, v61
	v_fmac_f32_e32 v68, 0xba800000, v61
	v_mul_f32_e32 v74, v68, v68
	v_mul_f32_e32 v76, v70, v70
	v_mul_f32_e32 v48, v64, v64
	v_mul_f32_e32 v46, v60, v60
	v_pk_add_f32 v[74:75], v[74:75], v[76:77]
	v_pk_add_f32 v[46:47], v[48:49], v[46:47]
	v_mov_b32_e32 v69, v70
	v_pk_add_f32 v[46:47], v[74:75], v[46:47]
	s_nop 0
	v_add_f32_e32 v46, v46, v47
	s_nop 1
	v_add_f32_dpp v46, v46, v46 quad_perm:[1,0,3,2] row_mask:0xf bank_mask:0xf
	s_nop 1
	v_add_f32_dpp v46, v46, v46 quad_perm:[2,3,0,1] row_mask:0xf bank_mask:0xf
	s_nop 1
	v_add_f32_dpp v46, v46, v46 row_half_mirror row_mask:0xf bank_mask:0xf
	s_nop 1
	v_add_f32_dpp v46, v46, v46 row_mirror row_mask:0xf bank_mask:0xf
	s_nop 1
	v_add_f32_dpp v46, v46, v46 row_bcast:15 row_mask:0xa bank_mask:0xf
	s_nop 1
	v_add_f32_dpp v46, v46, v46 row_bcast:31 row_mask:0xc bank_mask:0xf
	s_nop 1
	v_readlane_b32 s100, v46, 63
	s_nop 1
	v_mov_b32_e32 v46, s100
	v_fmamk_f32 v46, v46, 0x3a800000, v56
	v_mul_f32_e32 v47, 0x4f800000, v46
	v_cmp_gt_f32_e32 vcc, s5, v46
	s_nop 1
	v_cndmask_b32_e32 v46, v46, v47, vcc
	v_sqrt_f32_e32 v47, v46
	s_nop 0
	v_add_u32_e32 v48, -1, v47
	v_fma_f32 v49, -v48, v47, v46
	v_cmp_ge_f32_e64 s[0:1], 0, v49
	v_add_u32_e32 v49, 1, v47
	s_nop 0
	v_cndmask_b32_e64 v48, v47, v48, s[0:1]
	v_fma_f32 v47, -v49, v47, v46
	v_cmp_lt_f32_e64 s[0:1], 0, v47
	s_nop 1
	v_cndmask_b32_e64 v47, v48, v49, s[0:1]
	v_mul_f32_e32 v48, 0x37800000, v47
	v_cndmask_b32_e32 v47, v47, v48, vcc
	v_cmp_class_f32_e32 vcc, v46, v57
	s_nop 1
	v_cndmask_b32_e32 v46, v47, v46, vcc
	v_div_scale_f32 v47, s[0:1], v46, v46, 1.0
	v_rcp_f32_e32 v48, v47
	s_nop 0
	v_fma_f32 v49, -v47, v48, 1.0
	v_fmac_f32_e32 v48, v49, v48
	v_div_scale_f32 v49, vcc, 1.0, v46, 1.0
	v_mul_f32_e32 v61, v49, v48
	v_fma_f32 v65, -v47, v61, v49
	v_fmac_f32_e32 v61, v65, v48
	v_fma_f32 v47, -v47, v61, v49
	v_div_fmas_f32 v47, v47, v48, v61
	v_div_fixup_f32 v46, v47, v46, 1.0
	v_pk_mul_f32 v[58:59], v[58:59], v[46:47] op_sel_hi:[1,0]
	v_pk_mul_f32 v[42:43], v[42:43], v[46:47] op_sel_hi:[1,0]
	v_lshl_add_u64 v[48:49], s[2:3], 0, v[32:33]
	v_pk_fma_f32 v[42:43], v[2:3], v[42:43], v[6:7]
	v_pk_fma_f32 v[58:59], v[0:1], v[58:59], v[4:5]
	v_pk_mul_f32 v[44:45], v[44:45], v[46:47] op_sel_hi:[1,0]
	v_cvt_pk_bf16_f32 v58, v58, v59
	v_cvt_pk_bf16_f32 v59, v42, v43
	v_add_co_u32_e32 v42, vcc, s11, v48
	v_pk_fma_f32 v[44:45], v[18:19], v[44:45], v[22:23]
	s_nop 0
	v_addc_co_u32_e32 v43, vcc, 0, v49, vcc
	global_store_dwordx2 v[42:43], v[58:59], off
	v_pk_mul_f32 v[48:49], v[62:63], v[46:47] op_sel_hi:[1,0]
	v_pk_mul_f32 v[58:59], v[72:73], v[46:47] op_sel_hi:[1,0]
	v_pk_fma_f32 v[48:49], v[8:9], v[48:49], v[12:13]
	v_pk_fma_f32 v[58:59], v[10:11], v[58:59], v[14:15]
	v_cvt_pk_bf16_f32 v48, v48, v49
	v_cvt_pk_bf16_f32 v49, v58, v59
	global_store_dwordx2 v[42:43], v[48:49], off offset:512
	v_pk_mul_f32 v[48:49], v[66:67], v[46:47] op_sel_hi:[1,0]
	v_mov_b32_e32 v65, v60
	v_pk_fma_f32 v[48:49], v[16:17], v[48:49], v[20:21]
	s_add_u32 s2, s2, 0x4000
	v_cvt_pk_bf16_f32 v48, v48, v49
	v_cvt_pk_bf16_f32 v49, v44, v45
	v_pk_mul_f32 v[44:45], v[68:69], v[46:47] op_sel_hi:[1,0]
	v_pk_mul_f32 v[46:47], v[64:65], v[46:47] op_sel_hi:[1,0]
	v_pk_fma_f32 v[44:45], v[24:25], v[44:45], v[28:29]
	v_pk_fma_f32 v[46:47], v[26:27], v[46:47], v[30:31]
	s_addc_u32 s3, s3, 0
	v_cvt_pk_bf16_f32 v44, v44, v45
	v_cvt_pk_bf16_f32 v45, v46, v47
	s_add_u32 s6, s6, 0x4000
	global_store_dwordx2 v[42:43], v[48:49], off offset:1024
	global_store_dwordx2 v[42:43], v[44:45], off offset:1536
	s_addc_u32 s7, s7, 0
	s_add_i32 s4, s4, 8
	s_andn2_b64 vcc, exec, s[8:9]
	s_waitcnt vmcnt(4)
	v_mov_b32_e32 v48, v34
	v_mov_b32_e32 v49, v35
	v_mov_b32_e32 v46, v36
	v_mov_b32_e32 v47, v37
	v_mov_b32_e32 v44, v38
	v_mov_b32_e32 v45, v39
	v_mov_b32_e32 v42, v40
	v_mov_b32_e32 v43, v41
	s_cbranch_vccz .LBB0_445

; __device__ __forceinline__ f32x4 unpack4(u32x2 u) { return (f32x4){__uint_as_float(u.x << 16), __uint_as_float(u.x & 0xffff0000u), __uint_as_float(u.y << 16), __uint_as_float(u.y & 0xffff0000u)}; }
; __device__ __forceinline__ u32x2 pack4(f32x4 v) { u32x2 r; r.x = cvt_pk_bf16(v.x, v.y); r.y = cvt_pk_bf16(v.z, v.w); return r; }
; __device__ __forceinline__ void ln_pass(const bf16_t* PRE, const float* g, const float* b, float* Hf, bf16_t* HB, int gw, int ngw, int lane, int row_end = MT) {
;     ...
;     while (row < row_end) {
;         const int nrow = row + ngw;
;         if (nrow < row_end) {
; #pragma unroll
;             for (int j = 0; j < 4; ++j) qn[j] = *(const u32x2*)(PRE + (size_t)nrow * D + 4 * lane + 256 * j);
;         }
;         f32x4 v[4]; float s = 0.f;
; #pragma unroll
;         for (int j = 0; j < 4; ++j) { v[j] = unpack4(q[j]); s += (v[j].x + v[j].y) + (v[j].z + v[j].w); }
;         const float mean = wave_sum(s) * (1.f / D); float s2 = 0.f;
; #pragma unroll
;         for (int j = 0; j < 4; ++j) { v[j] = v[j] - mean; s2 += (v[j].x * v[j].x + v[j].y * v[j].y) + (v[j].z * v[j].z + v[j].w * v[j].w); }
;         const float rstd = 1.0f / sqrtf(wave_sum(s2) * (1.f / D) + LN_EPS);
; #pragma unroll
;         for (int j = 0; j < 4; ++j) { const f32x4 o = v[j] * rstd * gv[j] + bv[j];
;             if (Hf) *(f32x4*)(Hf + (size_t)row * D + 256 * j + 4 * lane) = o;
;             if (HB) *(u32x2*)(HB + (size_t)row * D + 256 * j + 4 * lane) = pack4(o); }
; #pragma unroll
;         for (int j = 0; j < 4; ++j) q[j] = qn[j];
;         row = nrow;
.LBB0_1280:
	s_waitcnt vmcnt(7)
	v_lshlrev_b32_e32 v59, 16, v49
	v_lshlrev_b32_e32 v58, 16, v48
	v_and_b32_e32 v49, 0xffff0000, v49
	v_and_b32_e32 v48, 0xffff0000, v48
	s_waitcnt vmcnt(6)
	v_lshlrev_b32_e32 v63, 16, v47
	v_lshlrev_b32_e32 v62, 16, v46
	v_and_b32_e32 v47, 0xffff0000, v47
	v_and_b32_e32 v46, 0xffff0000, v46
	v_pk_add_f32 v[60:61], v[58:59], v[48:49]
	v_pk_add_f32 v[64:65], v[62:63], v[46:47]
	v_add_f32_e32 v60, v60, v61
	v_pk_add_f32 v[64:65], v[64:65], v[64:65] op_sel_hi:[0,1]
	s_waitcnt vmcnt(5)
	v_lshlrev_b32_e32 v66, 16, v44
	v_and_b32_e32 v67, 0xffff0000, v44
	v_lshlrev_b32_e32 v44, 16, v45
	v_and_b32_e32 v45, 0xffff0000, v45
	v_add_f32_e32 v61, 0, v60
	v_add_f32_e32 v69, v66, v67
	v_add_f32_e32 v71, v44, v45
	s_waitcnt vmcnt(4)
	v_lshlrev_b32_e32 v68, 16, v42
	v_and_b32_e32 v70, 0xffff0000, v42
	v_lshlrev_b32_e32 v64, 16, v43
	v_and_b32_e32 v60, 0xffff0000, v43
	v_pk_add_f32 v[42:43], v[68:69], v[70:71]
	v_pk_add_f32 v[72:73], v[64:65], v[60:61]
	s_nop 0
	v_pk_add_f32 v[42:43], v[42:43], v[72:73]
	s_nop 0
	v_add_f32_e32 v42, v42, v43
	s_nop 1
	v_add_f32_dpp v42, v42, v42 quad_perm:[1,0,3,2] row_mask:0xf bank_mask:0xf
	s_nop 1
	v_add_f32_dpp v42, v42, v42 quad_perm:[2,3,0,1] row_mask:0xf bank_mask:0xf
	s_nop 1
	v_add_f32_dpp v42, v42, v42 row_half_mirror row_mask:0xf bank_mask:0xf
	s_nop 1
	v_add_f32_dpp v42, v42, v42 row_mirror row_mask:0xf bank_mask:0xf
	s_nop 1
	v_add_f32_dpp v42, v42, v42 row_bcast:15 row_mask:0xa bank_mask:0xf
	s_nop 1
	v_add_f32_dpp v42, v42, v42 row_bcast:31 row_mask:0xc bank_mask:0xf
	s_nop 1
	v_readlane_b32 s100, v42, 63
	s_nop 1
	v_mov_b32_e32 v61, s100
	v_fmac_f32_e32 v48, 0xba800000, v61
	v_fmac_f32_e32 v49, 0xba800000, v61
	v_fmac_f32_e32 v59, 0xba800000, v61
	v_fmac_f32_e32 v58, 0xba800000, v61
	v_mov_b32_e32 v42, v59
	v_mov_b32_e32 v43, v49
	v_mov_b32_e32 v59, v48
	v_pk_mul_f32 v[72:73], v[42:43], v[42:43]
	v_pk_mul_f32 v[48:49], v[58:59], v[58:59]
	v_fmac_f32_e32 v46, 0xba800000, v61
	v_fmac_f32_e32 v47, 0xba800000, v61
	v_fmac_f32_e32 v63, 0xba800000, v61
	v_pk_mov_b32 v[74:75], v[48:49], v[72:73] op_sel:[1,0]
	v_mov_b32_e32 v49, v73
	v_fmac_f32_e32 v62, 0xba800000, v61
	v_mov_b32_e32 v72, v63
	v_mov_b32_e32 v73, v47
	v_mov_b32_e32 v63, v46
	v_pk_add_f32 v[48:49], v[74:75], v[48:49]
	v_pk_mul_f32 v[74:75], v[72:73], v[72:73]
	v_pk_mul_f32 v[46:47], v[62:63], v[62:63]
	v_fmac_f32_e32 v66, 0xba800000, v61
	v_pk_mov_b32 v[76:77], v[46:47], v[74:75] op_sel:[1,0]
	v_mov_b32_e32 v47, v75
	v_pk_add_f32 v[46:47], v[76:77], v[46:47]
	v_fmac_f32_e32 v67, 0xba800000, v61
	v_pk_add_f32 v[46:47], v[46:47], v[46:47] op_sel_hi:[0,1]
	v_fmac_f32_e32 v44, 0xba800000, v61
	v_mul_f32_e32 v46, v66, v66
	v_fmac_f32_e32 v45, 0xba800000, v61
	v_pk_fma_f32 v[74:75], v[66:67], v[66:67], v[46:47] op_sel_hi:[1,1,0]
	v_mul_f32_e32 v46, v44, v44
	v_pk_add_f32 v[48:49], v[48:49], v[48:49] op_sel_hi:[0,1]
	v_pk_fma_f32 v[76:77], v[44:45], v[44:45], v[46:47] op_sel_hi:[1,1,0]
	v_fmac_f32_e32 v60, 0xba800000, v61
	v_fmac_f32_e32 v64, 0xba800000, v61
	v_fmac_f32_e32 v70, 0xba800000, v61
	v_fmac_f32_e32 v68, 0xba800000, v61
	v_mul_f32_e32 v74, v68, v68
	v_mul_f32_e32 v76, v70, v70
	v_mul_f32_e32 v48, v64, v64
	v_mul_f32_e32 v46, v60, v60
	v_pk_add_f32 v[74:75], v[74:75], v[76:77]
	v_pk_add_f32 v[46:47], v[48:49], v[46:47]
	v_mov_b32_e32 v69, v70
	v_pk_add_f32 v[46:47], v[74:75], v[46:47]
	s_nop 0
	v_add_f32_e32 v46, v46, v47
	s_nop 1
	v_add_f32_dpp v46, v46, v46 quad_perm:[1,0,3,2] row_mask:0xf bank_mask:0xf
	s_nop 1
	v_add_f32_dpp v46, v46, v46 quad_perm:[2,3,0,1] row_mask:0xf bank_mask:0xf
	s_nop 1
	v_add_f32_dpp v46, v46, v46 row_half_mirror row_mask:0xf bank_mask:0xf
	s_nop 1
	v_add_f32_dpp v46, v46, v46 row_mirror row_mask:0xf bank_mask:0xf
	s_nop 1
	v_add_f32_dpp v46, v46, v46 row_bcast:15 row_mask:0xa bank_mask:0xf
	s_nop 1
	v_add_f32_dpp v46, v46, v46 row_bcast:31 row_mask:0xc bank_mask:0xf
	s_nop 1
	v_readlane_b32 s100, v46, 63
	s_nop 1
	v_mov_b32_e32 v46, s100
	v_fmamk_f32 v46, v46, 0x3a800000, v56
	v_mul_f32_e32 v47, 0x4f800000, v46
	v_cmp_gt_f32_e32 vcc, s5, v46
	s_nop 1
	v_cndmask_b32_e32 v46, v46, v47, vcc
	v_sqrt_f32_e32 v47, v46
	s_nop 0
	v_add_u32_e32 v48, -1, v47
	v_fma_f32 v49, -v48, v47, v46
	v_cmp_ge_f32_e64 s[0:1], 0, v49
	v_add_u32_e32 v49, 1, v47
	s_nop 0
	v_cndmask_b32_e64 v48, v47, v48, s[0:1]
	v_fma_f32 v47, -v49, v47, v46
	v_cmp_lt_f32_e64 s[0:1], 0, v47
	s_nop 1
	v_cndmask_b32_e64 v47, v48, v49, s[0:1]
	v_mul_f32_e32 v48, 0x37800000, v47
	v_cndmask_b32_e32 v47, v47, v48, vcc
	v_cmp_class_f32_e32 vcc, v46, v57
	s_nop 1
	v_cndmask_b32_e32 v46, v47, v46, vcc
	v_div_scale_f32 v47, s[0:1], v46, v46, 1.0
	v_rcp_f32_e32 v48, v47
	s_nop 0
	v_fma_f32 v49, -v47, v48, 1.0
	v_fmac_f32_e32 v48, v49, v48
	v_div_scale_f32 v49, vcc, 1.0, v46, 1.0
	v_mul_f32_e32 v61, v49, v48
	v_fma_f32 v65, -v47, v61, v49
	v_fmac_f32_e32 v61, v65, v48
	v_fma_f32 v47, -v47, v61, v49
	v_div_fmas_f32 v47, v47, v48, v61
	v_div_fixup_f32 v46, v47, v46, 1.0
	v_pk_mul_f32 v[58:59], v[58:59], v[46:47] op_sel_hi:[1,0]
	v_pk_mul_f32 v[42:43], v[42:43], v[46:47] op_sel_hi:[1,0]
	v_lshl_add_u64 v[48:49], s[2:3], 0, v[32:33]
	v_pk_fma_f32 v[42:43], v[2:3], v[42:43], v[10:11]
	v_pk_fma_f32 v[58:59], v[0:1], v[58:59], v[8:9]
	v_pk_mul_f32 v[44:45], v[44:45], v[46:47] op_sel_hi:[1,0]
	v_cvt_pk_bf16_f32 v58, v58, v59
	v_cvt_pk_bf16_f32 v59, v42, v43
	v_add_co_u32_e32 v42, vcc, s11, v48
	v_pk_fma_f32 v[44:45], v[18:19], v[44:45], v[26:27]
	s_nop 0
	v_addc_co_u32_e32 v43, vcc, 0, v49, vcc
	global_store_dwordx2 v[42:43], v[58:59], off
	v_pk_mul_f32 v[48:49], v[62:63], v[46:47] op_sel_hi:[1,0]
	v_pk_mul_f32 v[58:59], v[72:73], v[46:47] op_sel_hi:[1,0]
	v_pk_fma_f32 v[48:49], v[4:5], v[48:49], v[12:13]
	v_pk_fma_f32 v[58:59], v[6:7], v[58:59], v[14:15]
	v_cvt_pk_bf16_f32 v48, v48, v49
	v_cvt_pk_bf16_f32 v49, v58, v59
	global_store_dwordx2 v[42:43], v[48:49], off offset:512
	v_pk_mul_f32 v[48:49], v[66:67], v[46:47] op_sel_hi:[1,0]
	v_mov_b32_e32 v65, v60
	v_pk_fma_f32 v[48:49], v[16:17], v[48:49], v[24:25]
	s_add_u32 s2, s2, 0x4000
	v_cvt_pk_bf16_f32 v48, v48, v49
	v_cvt_pk_bf16_f32 v49, v44, v45
	v_pk_mul_f32 v[44:45], v[68:69], v[46:47] op_sel_hi:[1,0]
	v_pk_mul_f32 v[46:47], v[64:65], v[46:47] op_sel_hi:[1,0]
	v_pk_fma_f32 v[44:45], v[20:21], v[44:45], v[28:29]
	v_pk_fma_f32 v[46:47], v[22:23], v[46:47], v[30:31]
	s_addc_u32 s3, s3, 0
	v_cvt_pk_bf16_f32 v44, v44, v45
	v_cvt_pk_bf16_f32 v45, v46, v47
	s_add_u32 s6, s6, 0x4000
	global_store_dwordx2 v[42:43], v[48:49], off offset:1024
	global_store_dwordx2 v[42:43], v[44:45], off offset:1536
	s_addc_u32 s7, s7, 0
	s_add_i32 s4, s4, 8
	s_andn2_b64 vcc, exec, s[8:9]
	s_waitcnt vmcnt(4)
	v_mov_b32_e32 v48, v34
	v_mov_b32_e32 v49, v35
	v_mov_b32_e32 v46, v36
	v_mov_b32_e32 v47, v37
	v_mov_b32_e32 v44, v38
	v_mov_b32_e32 v45, v39
	v_mov_b32_e32 v42, v40
	v_mov_b32_e32 v43, v41
	s_cbranch_vccz .LBB0_1283
